# GEMM phase prologues de-serialised: the K-tile-1 LDS-DMA batch is issued before the first wait+barrier (vmcnt 2 -> 8) in all 13 GEMM bodies
# baseline (speedup 1.0000x reference)
; #define PG8_STAGE(bufoff, gbase, voff) do { _Pragma("unroll") for (int _i = 0; _i < 2; ++_i) \
;         __builtin_amdgcn_global_load_lds((const unsigned*)((const char*)(gbase) + (voff)[_i]), (PG8_LAS unsigned*)(lds + (bufoff) + ldsw + _i * 8192), 16, 0, 0); } while (0)
; #define PG8_WAIT_V(n) asm volatile("s_waitcnt vmcnt(" #n ")" ::: "memory")
; #define PG8_BAR __builtin_amdgcn_s_barrier()
; template <class Epi, class Sched, bool ALIGN_EPI = false, bool SP2 = false>
; __device__ __forceinline__ void gemm_phase(PG8_LAS unsigned char* lds, const Gemm g, const Sched& S, const Epi& E) {
;     ...
;         PG8_STAGE(PG8_SB(0, 0), cB, voffB); PG8_STAGE(PG8_SB(0, 1), cB + hstepB, voffB); PG8_STAGE(PG8_SA(0, 0), cA, voffA); PG8_STAGE(PG8_SA(0, 1), cA + hstepA, voffA);
;         if (wr == 1) PG8_BAR;
;         PG8_WAIT_V(2); PG8_BAR;
;         PG8_STAGE(PG8_SB(1, 0), cB + kstep, voffB); PG8_STAGE(PG8_SA(1, 0), cA + kstep, voffA); PG8_STAGE(PG8_SB(1, 1), cB + hstepB + kstep, voffB);
;         PG8_WAIT_V(6); PG8_BAR;
.LBB0_397:
	v_readlane_b32 s8, v253, 50
	v_mov_b32_e32 v135, v1
	v_readlane_b32 s9, v253, 51
	v_mov_b32_e32 v131, v1
	v_readlane_b32 s18, v253, 46
	v_lshl_add_u64 v[10:11], s[8:9], 0, v[134:135]
	v_lshl_add_u64 v[12:13], s[8:9], 0, v[130:131]
	v_mov_b32_e32 v137, v1
	v_readlane_b32 s19, v253, 47
	s_add_i32 m0, s68, 0x18000
	v_lshl_add_u64 v[10:11], v[10:11], 0, s[20:21]
	v_lshl_add_u64 v[14:15], s[18:19], 0, v[136:137]
	v_mov_b32_e32 v133, v1
	global_load_lds_dwordx4 v[10:11], off
	v_lshl_add_u64 v[10:11], v[12:13], 0, s[20:21]
	s_add_i32 m0, s68, 0x1a000
	s_add_i32 s79, s68, 0x8000
	v_lshl_add_u64 v[16:17], s[18:19], 0, v[132:133]
	global_load_lds_dwordx4 v[10:11], off
	v_lshl_add_u64 v[10:11], v[14:15], 0, s[20:21]
	s_mov_b32 m0, s79
	s_add_i32 s94, s68, 0xa000
	v_readlane_b32 s22, v253, 52
	global_load_lds_dwordx4 v[10:11], off
	v_lshl_add_u64 v[10:11], v[16:17], 0, s[20:21]
	s_mov_b32 m0, s94
	v_readlane_b32 s23, v253, 53
	global_load_lds_dwordx4 v[10:11], off
	s_add_i32 m0, s68, 0x1c000
	v_lshl_add_u64 v[10:11], s[22:23], 0, v[134:135]
	global_load_lds_dwordx4 v[10:11], off
	v_lshl_add_u64 v[10:11], s[22:23], 0, v[130:131]
	s_add_i32 m0, s68, 0x1e000
	v_and_b32_e32 v9, 15, v3
	global_load_lds_dwordx4 v[10:11], off
	v_lshrrev_b32_e32 v10, 1, v3
	v_and_b32_e32 v10, 24, v10
	v_lshlrev_b32_e32 v11, 1, v10
	v_lshlrev_b32_e32 v3, 2, v3
	s_lshl_b32 s5, s5, 5
	v_lshl_or_b32 v0, s6, 6, v9
	v_lshl_or_b32 v9, v9, 6, v11
	s_lshl_b32 s6, s6, 13
	v_and_b32_e32 v3, 32, v3
	s_and_b32 s5, s5, 0x60
	v_bitop3_b32 v11, v9, s6, v3 bitop3:0xde
	s_lshl_b32 s6, s5, 7
	v_bitop3_b32 v142, v9, s6, v3 bitop3:0xde
	v_lshlrev_b32_e32 v3, 14, v7
	v_and_b32_e32 v3, 0xffff8000, v3
	v_lshl_add_u32 v3, v6, 11, v3
	v_and_b32_e32 v6, 1, v7
	v_lshl_or_b32 v3, v6, 6, v3
	v_lshl_add_u32 v138, v8, 1, v3
	v_lshlrev_b32_e32 v3, 14, v2
	v_and_b32_e32 v3, 0xffff8000, v3
	s_waitcnt vmcnt(8)
	s_barrier
	s_waitcnt vmcnt(6)
	s_cmpk_lt_u32 s4, 0x100
	v_or_b32_e32 v143, s5, v10
	v_lshl_add_u32 v3, v4, 11, v3
	v_and_b32_e32 v2, 1, v2
	v_readlane_b32 s4, v253, 42
	v_lshl_or_b32 v2, v2, 6, v3
	v_readlane_b32 s5, v253, 43
	s_cselect_b64 s[40:41], -1, 0
	v_mov_b32_e32 v139, v1
	v_lshl_add_u32 v140, v5, 1, v2
	v_mov_b32_e32 v141, v1
	s_mov_b32 s95, 0
	v_add_u32_e32 v144, 0, v11
	v_readlane_b32 s13, v253, 55
	s_mov_b32 s22, s4
	s_mov_b64 s[4:5], s[8:9]
	s_mov_b64 s[6:7], s[18:19]
	s_barrier
	s_branch .LBB0_400

; #define PG8_STAGE(bufoff, gbase, voff) do { _Pragma("unroll") for (int _i = 0; _i < 2; ++_i) \
;         __builtin_amdgcn_global_load_lds((const unsigned*)((const char*)(gbase) + (voff)[_i]), (PG8_LAS unsigned*)(lds + (bufoff) + ldsw + _i * 8192), 16, 0, 0); } while (0)
; #define PG8_WAIT_V(n) asm volatile("s_waitcnt vmcnt(" #n ")" ::: "memory")
; #define PG8_BAR __builtin_amdgcn_s_barrier()
; template <class Epi, class Sched, bool ALIGN_EPI = false, bool SP2 = false>
; __device__ __forceinline__ void gemm_phase(PG8_LAS unsigned char* lds, const Gemm g, const Sched& S, const Epi& E) {
;     ...
;         PG8_STAGE(PG8_SB(0, 0), cB, voffB); PG8_STAGE(PG8_SB(0, 1), cB + hstepB, voffB); PG8_STAGE(PG8_SA(0, 0), cA, voffA); PG8_STAGE(PG8_SA(0, 1), cA + hstepA, voffA);
;         if (wr == 1) PG8_BAR;
;         PG8_WAIT_V(2); PG8_BAR;
;         PG8_STAGE(PG8_SB(1, 0), cB + kstep, voffB); PG8_STAGE(PG8_SA(1, 0), cA + kstep, voffA); PG8_STAGE(PG8_SB(1, 1), cB + hstepB + kstep, voffB);
;         PG8_WAIT_V(6); PG8_BAR;
.LBB0_466:
	v_readlane_b32 s18, v254, 12
	v_mov_b32_e32 v133, v1
	v_readlane_b32 s19, v254, 13
	v_readlane_b32 s24, v255, 28
	v_mov_b32_e32 v131, v1
	v_lshl_add_u64 v[10:11], s[18:19], 0, v[132:133]
	v_readlane_b32 s48, v254, 8
	v_readlane_b32 s25, v255, 29
	s_add_u32 s24, s24, 0x2000
	v_lshl_add_u64 v[12:13], s[18:19], 0, v[130:131]
	v_readlane_b32 s49, v254, 9
	s_addc_u32 s25, s25, 0
	s_add_i32 m0, s9, 0x18000
	v_lshl_add_u64 v[10:11], v[10:11], 0, s[20:21]
	v_lshl_add_u64 v[14:15], s[48:49], 0, v[132:133]
	global_load_lds_dwordx4 v[10:11], off
	v_lshl_add_u64 v[10:11], v[12:13], 0, s[20:21]
	s_add_i32 m0, s9, 0x1a000
	s_add_i32 s26, s9, 0x8000
	v_lshl_add_u64 v[16:17], s[48:49], 0, v[130:131]
	global_load_lds_dwordx4 v[10:11], off
	v_lshl_add_u64 v[10:11], v[14:15], 0, s[20:21]
	s_mov_b32 m0, s26
	s_add_i32 s27, s9, 0xa000
	v_readlane_b32 s28, v254, 14
	global_load_lds_dwordx4 v[10:11], off
	v_lshl_add_u64 v[10:11], v[16:17], 0, s[20:21]
	s_mov_b32 m0, s27
	v_readlane_b32 s29, v254, 15
	global_load_lds_dwordx4 v[10:11], off
	s_add_i32 m0, s9, 0x1c000
	v_lshl_add_u64 v[10:11], s[28:29], 0, v[132:133]
	global_load_lds_dwordx4 v[10:11], off
	v_lshl_add_u64 v[10:11], s[28:29], 0, v[130:131]
	s_add_i32 m0, s9, 0x1e000
	v_bfe_u32 v14, v0, 4, 2
	global_load_lds_dwordx4 v[10:11], off
	v_and_b32_e32 v15, 15, v0
	s_lshl_b32 s7, s6, 6
	v_lshlrev_b32_e32 v11, 4, v14
	v_lshlrev_b32_e32 v0, 2, v0
	s_lshl_b32 s5, s5, 5
	v_or_b32_e32 v10, s7, v15
	v_lshl_or_b32 v11, v15, 6, v11
	s_lshl_b32 s6, s6, 13
	v_and_b32_e32 v0, 32, v0
	s_and_b32 s5, s5, 0x60
	v_bitop3_b32 v16, v11, s6, v0 bitop3:0xde
	s_lshl_b32 s6, s5, 7
	v_or_b32_e32 v12, 16, v10
	v_bitop3_b32 v0, v11, s6, v0 bitop3:0xde
	v_ashrrev_i32_e32 v11, 31, v10
	v_ashrrev_i32_e32 v13, 31, v12
	s_cmpk_lt_u32 s4, 0x100
	v_lshlrev_b64 v[134:135], 12, v[10:11]
	v_lshlrev_b64 v[136:137], 12, v[12:13]
	v_or_b32_e32 v12, 32, v10
	v_or_b32_e32 v10, 48, v10
	s_cselect_b64 s[46:47], -1, 0
	v_ashrrev_i32_e32 v11, 31, v10
	s_addk_i32 s7, 0x80
	s_movk_i32 s6, 0xb00
	v_lshlrev_b64 v[140:141], 12, v[10:11]
	v_or_b32_e32 v10, s7, v15
	v_lshrrev_b32_e32 v7, 1, v7
	v_mul_lo_u32 v6, v6, s6
	s_mov_b32 s7, 0xb000
	v_lshl_or_b32 v172, v14, 2, s5
	v_mad_u64_u32 v[6:7], s[4:5], v7, s7, v[6:7]
	v_or_b32_e32 v6, v6, v8
	v_ashrrev_i32_e32 v13, 31, v12
	v_add_lshl_u32 v6, v6, v9, 1
	v_mov_b32_e32 v7, v1
	s_mov_b64 s[28:29], 0xb0080
	v_lshlrev_b64 v[138:139], 12, v[12:13]
	v_or_b32_e32 v12, 16, v10
	v_lshl_add_u64 v[150:151], v[6:7], 0, s[28:29]
	v_lshrrev_b32_e32 v6, 1, v2
	v_mul_lo_u32 v2, v3, s6
	v_ashrrev_i32_e32 v11, 31, v10
	v_ashrrev_i32_e32 v13, 31, v12
	v_mad_u64_u32 v[2:3], s[4:5], v6, s7, v[2:3]
	s_waitcnt vmcnt(8)
	s_barrier
	s_waitcnt vmcnt(6)
	v_lshlrev_b64 v[142:143], 12, v[10:11]
	v_lshlrev_b64 v[144:145], 12, v[12:13]
	v_or_b32_e32 v12, 32, v10
	v_or_b32_e32 v10, 48, v10
	v_or_b32_e32 v2, v2, v4
	v_readlane_b32 s4, v254, 32
	v_ashrrev_i32_e32 v13, 31, v12
	v_ashrrev_i32_e32 v11, 31, v10
	v_add_lshl_u32 v2, v2, v5, 1
	v_mov_b32_e32 v3, v1
	v_readlane_b32 s5, v254, 33
	v_lshlrev_b64 v[146:147], 12, v[12:13]
	v_lshlrev_b64 v[148:149], 12, v[10:11]
	v_lshl_add_u64 v[152:153], v[2:3], 0, s[28:29]
	s_mov_b32 s28, 0
	v_add_u32_e32 v173, 0, v16
	v_readlane_b32 s64, v254, 3
	s_mov_b32 s72, s4
	s_mov_b64 s[4:5], s[18:19]
	s_barrier
	s_branch .LBB0_469

; #define PG8_STAGE(bufoff, gbase, voff) do { _Pragma("unroll") for (int _i = 0; _i < 2; ++_i) \
;         __builtin_amdgcn_global_load_lds((const unsigned*)((const char*)(gbase) + (voff)[_i]), (PG8_LAS unsigned*)(lds + (bufoff) + ldsw + _i * 8192), 16, 0, 0); } while (0)
; #define PG8_WAIT_V(n) asm volatile("s_waitcnt vmcnt(" #n ")" ::: "memory")
; #define PG8_BAR __builtin_amdgcn_s_barrier()
; template <class Epi, class Sched, bool ALIGN_EPI = false, bool SP2 = false>
; __device__ __forceinline__ void gemm_phase(PG8_LAS unsigned char* lds, const Gemm g, const Sched& S, const Epi& E) {
;     ...
;         PG8_STAGE(PG8_SB(0, 0), cB, voffB); PG8_STAGE(PG8_SB(0, 1), cB + hstepB, voffB); PG8_STAGE(PG8_SA(0, 0), cA, voffA); PG8_STAGE(PG8_SA(0, 1), cA + hstepA, voffA);
;         if (wr == 1) PG8_BAR;
;         PG8_WAIT_V(2); PG8_BAR;
;         PG8_STAGE(PG8_SB(1, 0), cB + kstep, voffB); PG8_STAGE(PG8_SA(1, 0), cA + kstep, voffA); PG8_STAGE(PG8_SB(1, 1), cB + hstepB + kstep, voffB);
;         PG8_WAIT_V(6); PG8_BAR;
.LBB0_610:
	s_and_b32 s5, s5, 3
	s_add_i32 m0, s9, 0x18000
	v_lshl_add_u64 v[8:9], v[8:9], 0, s[20:21]
	s_lshl_b32 s26, s6, 6
	s_lshl_b32 s13, s6, 13
	s_lshl_b32 s27, s5, 5
	s_lshl_b32 s5, s5, 12
	global_load_lds_dwordx4 v[8:9], off
	v_lshl_add_u64 v[6:7], v[6:7], 0, s[20:21]
	s_add_i32 m0, s9, 0x1a000
	s_add_i32 s28, s9, 0x8000
	s_add_i32 s29, s9, 0xa000
	global_load_lds_dwordx4 v[6:7], off
	v_lshl_add_u64 v[2:3], v[2:3], 0, s[20:21]
	s_mov_b32 m0, s28
	s_add_u32 s6, s94, 0x40080
	global_load_lds_dwordx4 v[2:3], off
	v_lshl_add_u64 v[2:3], v[4:5], 0, s[20:21]
	s_mov_b32 m0, s29
	s_addc_u32 s7, s95, 0
	global_load_lds_dwordx4 v[2:3], off
	s_add_i32 m0, s9, 0x1c000
	v_lshl_add_u64 v[2:3], s[6:7], 0, v[132:133]
	global_load_lds_dwordx4 v[2:3], off
	v_lshl_add_u64 v[2:3], s[6:7], 0, v[136:137]
	s_add_i32 m0, s9, 0x1e000
	v_and_b32_e32 v139, 15, v10
	global_load_lds_dwordx4 v[2:3], off
	v_bfe_u32 v3, v10, 4, 2
	v_lshlrev_b32_e32 v2, 4, v3
	v_lshlrev_b32_e32 v5, 2, v10
	v_lshl_or_b32 v4, v139, 6, v2
	v_and_b32_e32 v5, 32, v5
	s_cmpk_lt_u32 s4, 0x100
	v_bitop3_b32 v156, v4, s5, v5 bitop3:0xde
	s_cselect_b64 s[46:47], -1, 0
	s_bitcmp0_b32 s4, 6
	v_readlane_b32 s4, v250, 50
	v_lshlrev_b32_e32 v138, 3, v3
	v_cmp_gt_u32_e64 s[40:41], 2, v3
	v_mov_b32_e32 v3, v1
	v_readlane_b32 s5, v250, 51
	s_waitcnt vmcnt(8)
	s_barrier
	s_waitcnt vmcnt(6)
	v_bitop3_b32 v6, v4, s13, v5 bitop3:0xde
	s_mov_b32 s13, 0
	v_lshl_add_u64 v[140:141], s[4:5], 0, v[2:3]
	v_readlane_b32 s4, v252, 28
	v_readlane_b32 s5, v252, 29
	s_cselect_b64 s[38:39], -1, 0
	v_or_b32_e32 v157, 16, v139
	v_lshl_add_u64 v[142:143], s[4:5], 0, v[2:3]
	v_readlane_b32 s4, v252, 30
	v_and_b32_e32 v2, 16, v2
	v_readlane_b32 s5, v252, 31
	v_or_b32_e32 v158, 32, v139
	v_or_b32_e32 v159, 48, v139
	v_lshl_add_u64 v[144:145], s[4:5], 0, v[2:3]
	v_readlane_b32 s4, v252, 32
	v_readlane_b32 s5, v252, 33
	v_mov_b32_e32 v149, v1
	v_mov_b32_e32 v151, v1
	v_lshl_add_u64 v[146:147], s[4:5], 0, v[2:3]
	v_lshlrev_b32_e32 v2, 14, v0
	v_and_b32_e32 v2, 0xffff8000, v2
	v_lshl_add_u32 v2, v11, 11, v2
	v_and_b32_e32 v0, 1, v0
	v_lshl_or_b32 v0, v0, 6, v2
	v_lshl_add_u32 v148, v12, 1, v0
	v_lshlrev_b32_e32 v0, 14, v13
	v_and_b32_e32 v0, 0xffff8000, v0
	v_lshl_add_u32 v0, v14, 11, v0
	v_and_b32_e32 v2, 1, v13
	v_lshl_or_b32 v0, v2, 6, v0
	v_lshl_add_u32 v150, v15, 1, v0
	v_add_u32_e32 v160, 0, v6
	s_barrier
	s_branch .LBB0_613

; #define PG8_STAGE(bufoff, gbase, voff) do { _Pragma("unroll") for (int _i = 0; _i < 2; ++_i) \
;         __builtin_amdgcn_global_load_lds((const unsigned*)((const char*)(gbase) + (voff)[_i]), (PG8_LAS unsigned*)(lds + (bufoff) + ldsw + _i * 8192), 16, 0, 0); } while (0)
; #define PG8_WAIT_V(n) asm volatile("s_waitcnt vmcnt(" #n ")" ::: "memory")
; #define PG8_BAR __builtin_amdgcn_s_barrier()
; template <class Epi, class Sched, bool ALIGN_EPI = false, bool SP2 = false>
; __device__ __forceinline__ void gemm_phase(PG8_LAS unsigned char* lds, const Gemm g, const Sched& S, const Epi& E) {
;     ...
;         PG8_STAGE(PG8_SB(0, 0), cB, voffB); PG8_STAGE(PG8_SB(0, 1), cB + hstepB, voffB); PG8_STAGE(PG8_SA(0, 0), cA, voffA); PG8_STAGE(PG8_SA(0, 1), cA + hstepA, voffA);
;         if (wr == 1) PG8_BAR;
;         PG8_WAIT_V(2); PG8_BAR;
;         PG8_STAGE(PG8_SB(1, 0), cB + kstep, voffB); PG8_STAGE(PG8_SA(1, 0), cA + kstep, voffA); PG8_STAGE(PG8_SB(1, 1), cB + hstepB + kstep, voffB);
;         PG8_WAIT_V(6); PG8_BAR;
.LBB0_948:
	v_bfe_u32 v18, v0, 4, 2
	v_and_b32_e32 v139, 15, v0
	s_waitcnt lgkmcnt(0)
	v_lshlrev_b32_e32 v19, 4, v18
	v_lshlrev_b32_e32 v20, 2, v0
	s_lshl_b32 s28, s4, 6
	v_lshl_or_b32 v19, v139, 6, v19
	s_lshl_b32 s4, s4, 13
	v_and_b32_e32 v20, 32, v20
	v_bitop3_b32 v21, v19, s4, v20 bitop3:0xde
	s_lshl_b32 s4, s5, 5
	s_and_b32 s29, s4, 0x60
	s_add_i32 m0, s13, 0x18000
	v_lshl_add_u64 v[8:9], v[8:9], 0, s[20:21]
	s_lshl_b32 s4, s29, 7
	global_load_lds_dwordx4 v[8:9], off
	v_lshl_add_u64 v[6:7], v[6:7], 0, s[20:21]
	s_add_i32 m0, s13, 0x1a000
	s_add_i32 s78, s13, 0x8000
	s_add_i32 s79, s13, 0xa000
	v_bitop3_b32 v150, v19, s4, v20 bitop3:0xde
	global_load_lds_dwordx4 v[6:7], off
	v_lshl_add_u64 v[2:3], v[2:3], 0, s[20:21]
	s_mov_b32 m0, s78
	s_add_u32 s4, s68, 0x18080
	global_load_lds_dwordx4 v[2:3], off
	v_lshl_add_u64 v[2:3], v[4:5], 0, s[20:21]
	s_mov_b32 m0, s79
	s_addc_u32 s5, s69, 0
	global_load_lds_dwordx4 v[2:3], off
	s_add_i32 m0, s13, 0x1c000
	v_lshl_add_u64 v[2:3], s[4:5], 0, v[132:133]
	global_load_lds_dwordx4 v[2:3], off
	v_lshl_add_u64 v[2:3], s[4:5], 0, v[136:137]
	s_add_i32 m0, s13, 0x1e000
	v_readlane_b32 s4, v252, 30
	global_load_lds_dwordx4 v[2:3], off
	v_and_b32_e32 v2, 16, v0
	v_mov_b32_e32 v3, v1
	v_readlane_b32 s5, v252, 31
	s_movk_i32 s6, 0xb00
	v_mul_lo_u32 v0, v12, s6
	v_lshl_add_u64 v[140:141], s[4:5], 0, v[2:3]
	v_readlane_b32 s4, v252, 32
	v_readlane_b32 s5, v252, 33
	s_mov_b32 s7, 0xb000
	s_mov_b64 s[18:19], 0xb0080
	v_lshl_add_u64 v[142:143], s[4:5], 0, v[2:3]
	v_lshrrev_b32_e32 v2, 1, v10
	v_mad_u64_u32 v[2:3], s[4:5], v2, s7, v[0:1]
	v_or_b32_e32 v0, v2, v11
	v_add_lshl_u32 v2, v0, v13, 1
	v_mov_b32_e32 v3, v1
	v_lshl_add_u64 v[144:145], v[2:3], 0, s[18:19]
	v_lshrrev_b32_e32 v2, 1, v14
	v_mul_lo_u32 v0, v16, s6
	v_mad_u64_u32 v[2:3], s[4:5], v2, s7, v[0:1]
	s_waitcnt vmcnt(8)
	s_barrier
	s_waitcnt vmcnt(6)
	s_cmpk_lt_u32 s22, 0x100
	v_or_b32_e32 v0, v2, v15
	s_cselect_b64 s[46:47], -1, 0
	s_lshr_b32 s94, s74, 3
	v_add_lshl_u32 v2, v0, v17, 1
	v_mov_b32_e32 v3, v1
	v_lshlrev_b32_e32 v138, 3, v18
	v_cmp_gt_u32_e64 s[38:39], 2, v18
	v_or_b32_e32 v151, 16, v139
	v_or_b32_e32 v152, 32, v139
	v_or_b32_e32 v153, 48, v139
	s_and_b32 s95, s74, 4
	s_add_i32 s59, s94, 1
	v_lshl_add_u64 v[146:147], v[2:3], 0, s[18:19]
	s_mov_b32 s64, 0
	v_add_u32_e32 v154, 0, v21
	s_barrier
	s_branch .LBB0_951

; #define PG8_STAGE(bufoff, gbase, voff) do { _Pragma("unroll") for (int _i = 0; _i < 2; ++_i) \
;         __builtin_amdgcn_global_load_lds((const unsigned*)((const char*)(gbase) + (voff)[_i]), (PG8_LAS unsigned*)(lds + (bufoff) + ldsw + _i * 8192), 16, 0, 0); } while (0)
; #define PG8_WAIT_V(n) asm volatile("s_waitcnt vmcnt(" #n ")" ::: "memory")
; #define PG8_BAR __builtin_amdgcn_s_barrier()
; template <class Epi, class Sched, bool ALIGN_EPI = false, bool SP2 = false>
; __device__ __forceinline__ void gemm_phase(PG8_LAS unsigned char* lds, const Gemm g, const Sched& S, const Epi& E) {
;     ...
;         PG8_STAGE(PG8_SB(0, 0), cB, voffB); PG8_STAGE(PG8_SB(0, 1), cB + hstepB, voffB); PG8_STAGE(PG8_SA(0, 0), cA, voffA); PG8_STAGE(PG8_SA(0, 1), cA + hstepA, voffA);
;         if (wr == 1) PG8_BAR;
;         PG8_WAIT_V(2); PG8_BAR;
;         PG8_STAGE(PG8_SB(1, 0), cB + kstep, voffB); PG8_STAGE(PG8_SA(1, 0), cA + kstep, voffA); PG8_STAGE(PG8_SB(1, 1), cB + hstepB + kstep, voffB);
;         PG8_WAIT_V(6); PG8_BAR;
.LBB0_1004:
	v_lshrrev_b32_e32 v12, 1, v2
	v_and_b32_e32 v12, 24, v12
	v_readlane_b32 s68, v254, 28
	v_and_b32_e32 v3, 15, v2
	v_lshlrev_b32_e32 v13, 1, v12
	v_lshlrev_b32_e32 v2, 2, v2
	s_lshl_b32 s5, s5, 5
	v_mov_b32_e32 v135, v1
	v_readlane_b32 s69, v254, 29
	v_lshl_or_b32 v0, s6, 6, v3
	v_lshl_or_b32 v3, v3, 6, v13
	s_lshl_b32 s6, s6, 13
	v_and_b32_e32 v2, 32, v2
	s_and_b32 s5, s5, 0x60
	v_lshl_add_u64 v[4:5], s[68:69], 0, v[134:135]
	v_mov_b32_e32 v131, v1
	v_readlane_b32 s72, v254, 24
	v_bitop3_b32 v13, v3, s6, v2 bitop3:0xde
	s_lshl_b32 s6, s5, 7
	v_lshl_add_u64 v[6:7], s[68:69], 0, v[130:131]
	v_mov_b32_e32 v137, v1
	v_readlane_b32 s73, v254, 25
	v_bitop3_b32 v138, v3, s6, v2 bitop3:0xde
	s_add_i32 m0, s33, 0x18000
	v_lshl_add_u64 v[2:3], v[4:5], 0, s[20:21]
	v_lshl_add_u64 v[8:9], s[72:73], 0, v[136:137]
	v_mov_b32_e32 v133, v1
	global_load_lds_dwordx4 v[2:3], off
	v_lshl_add_u64 v[2:3], v[6:7], 0, s[20:21]
	s_add_i32 m0, s33, 0x1a000
	s_add_i32 s27, s33, 0x8000
	v_lshl_add_u64 v[10:11], s[72:73], 0, v[132:133]
	global_load_lds_dwordx4 v[2:3], off
	v_lshl_add_u64 v[2:3], v[8:9], 0, s[20:21]
	s_mov_b32 m0, s27
	s_add_i32 s28, s33, 0xa000
	v_readlane_b32 s6, v254, 30
	global_load_lds_dwordx4 v[2:3], off
	v_lshl_add_u64 v[2:3], v[10:11], 0, s[20:21]
	s_mov_b32 m0, s28
	v_readlane_b32 s7, v254, 31
	global_load_lds_dwordx4 v[2:3], off
	s_add_i32 m0, s33, 0x1c000
	v_lshl_add_u64 v[2:3], s[6:7], 0, v[134:135]
	global_load_lds_dwordx4 v[2:3], off
	v_lshl_add_u64 v[2:3], s[6:7], 0, v[130:131]
	s_add_i32 m0, s33, 0x1e000
	s_cmpk_lt_u32 s4, 0x100
	global_load_lds_dwordx4 v[2:3], off
	s_waitcnt vmcnt(8)
	s_barrier
	s_waitcnt vmcnt(6)
	v_or_b32_e32 v139, s5, v12
	v_readlane_b32 s4, v254, 32
	s_cselect_b64 s[44:45], -1, 0
	s_mov_b32 s29, 0
	v_add_u32_e32 v140, 0, v13
	v_readlane_b32 s64, v254, 3
	s_mov_b32 s74, s4
	s_barrier
	v_readlane_b32 s5, v254, 33
	s_branch .LBB0_1007

; #define PG8_STAGE(bufoff, gbase, voff) do { _Pragma("unroll") for (int _i = 0; _i < 2; ++_i) \
;         __builtin_amdgcn_global_load_lds((const unsigned*)((const char*)(gbase) + (voff)[_i]), (PG8_LAS unsigned*)(lds + (bufoff) + ldsw + _i * 8192), 16, 0, 0); } while (0)
; #define PG8_WAIT_V(n) asm volatile("s_waitcnt vmcnt(" #n ")" ::: "memory")
; #define PG8_BAR __builtin_amdgcn_s_barrier()
; template <class Epi, class Sched, bool ALIGN_EPI = false, bool SP2 = false>
; __device__ __forceinline__ void gemm_phase(PG8_LAS unsigned char* lds, const Gemm g, const Sched& S, const Epi& E) {
;     ...
;         PG8_STAGE(PG8_SB(0, 0), cB, voffB); PG8_STAGE(PG8_SB(0, 1), cB + hstepB, voffB); PG8_STAGE(PG8_SA(0, 0), cA, voffA); PG8_STAGE(PG8_SA(0, 1), cA + hstepA, voffA);
;         if (wr == 1) PG8_BAR;
;         PG8_WAIT_V(2); PG8_BAR;
;         PG8_STAGE(PG8_SB(1, 0), cB + kstep, voffB); PG8_STAGE(PG8_SA(1, 0), cA + kstep, voffA); PG8_STAGE(PG8_SB(1, 1), cB + hstepB + kstep, voffB);
;         PG8_WAIT_V(6); PG8_BAR;
.LBB0_1290:
	v_lshrrev_b32_e32 v18, 1, v8
	v_and_b32_e32 v18, 24, v18
	v_readlane_b32 s8, v254, 42
	v_and_b32_e32 v9, 15, v8
	s_waitcnt lgkmcnt(0)
	v_lshlrev_b32_e32 v19, 1, v18
	v_lshlrev_b32_e32 v8, 2, v8
	s_lshl_b32 s5, s5, 5
	v_mov_b32_e32 v147, v1
	v_readlane_b32 s9, v254, 43
	v_lshl_or_b32 v0, s6, 6, v9
	v_lshl_or_b32 v9, v9, 6, v19
	s_lshl_b32 s6, s6, 13
	v_and_b32_e32 v8, 32, v8
	s_and_b32 s5, s5, 0x60
	v_lshl_add_u64 v[10:11], s[8:9], 0, v[146:147]
	v_mov_b32_e32 v143, v1
	v_readlane_b32 s18, v254, 38
	v_bitop3_b32 v19, v9, s6, v8 bitop3:0xde
	s_lshl_b32 s6, s5, 7
	v_lshl_add_u64 v[12:13], s[8:9], 0, v[142:143]
	v_mov_b32_e32 v149, v1
	v_readlane_b32 s19, v254, 39
	v_bitop3_b32 v162, v9, s6, v8 bitop3:0xde
	s_add_i32 m0, s68, 0x18000
	v_lshl_add_u64 v[8:9], v[10:11], 0, s[20:21]
	v_lshl_add_u64 v[14:15], s[18:19], 0, v[148:149]
	v_mov_b32_e32 v145, v1
	global_load_lds_dwordx4 v[8:9], off
	v_lshl_add_u64 v[8:9], v[12:13], 0, s[20:21]
	s_add_i32 m0, s68, 0x1a000
	s_add_i32 s74, s68, 0x8000
	v_lshl_add_u64 v[16:17], s[18:19], 0, v[144:145]
	global_load_lds_dwordx4 v[8:9], off
	v_lshl_add_u64 v[8:9], v[14:15], 0, s[20:21]
	s_mov_b32 m0, s74
	s_add_i32 s78, s68, 0xa000
	v_readlane_b32 s6, v254, 44
	global_load_lds_dwordx4 v[8:9], off
	v_lshl_add_u64 v[8:9], v[16:17], 0, s[20:21]
	s_mov_b32 m0, s78
	v_readlane_b32 s7, v254, 45
	global_load_lds_dwordx4 v[8:9], off
	s_add_i32 m0, s68, 0x1c000
	v_lshl_add_u64 v[8:9], s[6:7], 0, v[146:147]
	global_load_lds_dwordx4 v[8:9], off
	v_lshl_add_u64 v[8:9], s[6:7], 0, v[142:143]
	s_add_i32 m0, s68, 0x1e000
	s_cmpk_lt_u32 s4, 0x100
	global_load_lds_dwordx4 v[8:9], off
	v_lshlrev_b32_e32 v8, 14, v6
	v_and_b32_e32 v8, 0xffff8000, v8
	v_lshl_add_u32 v5, v5, 11, v8
	v_and_b32_e32 v6, 1, v6
	v_lshl_or_b32 v5, v6, 6, v5
	v_lshl_add_u32 v150, v7, 1, v5
	v_lshlrev_b32_e32 v5, 14, v2
	v_and_b32_e32 v5, 0xffff8000, v5
	s_waitcnt vmcnt(8)
	s_barrier
	s_waitcnt vmcnt(6)
	v_or_b32_e32 v163, s5, v18
	v_lshl_add_u32 v3, v3, 11, v5
	v_and_b32_e32 v2, 1, v2
	v_readlane_b32 s4, v254, 32
	v_lshl_or_b32 v2, v2, 6, v3
	v_readlane_b32 s5, v254, 33
	s_cselect_b64 s[40:41], -1, 0
	v_mov_b32_e32 v151, v1
	v_lshl_add_u32 v152, v4, 1, v2
	v_mov_b32_e32 v153, v1
	s_mov_b32 s79, 0
	v_add_u32_e32 v164, 0, v19
	v_readlane_b32 s13, v254, 3
	s_mov_b32 s22, s4
	s_mov_b64 s[4:5], s[8:9]
	s_mov_b64 s[6:7], s[18:19]
	s_barrier
	s_branch .LBB0_1293

; #define PG8_STAGE(bufoff, gbase, voff) do { _Pragma("unroll") for (int _i = 0; _i < 2; ++_i) \
;         __builtin_amdgcn_global_load_lds((const unsigned*)((const char*)(gbase) + (voff)[_i]), (PG8_LAS unsigned*)(lds + (bufoff) + ldsw + _i * 8192), 16, 0, 0); } while (0)
; #define PG8_WAIT_V(n) asm volatile("s_waitcnt vmcnt(" #n ")" ::: "memory")
; #define PG8_BAR __builtin_amdgcn_s_barrier()
; template <class Epi, class Sched, bool ALIGN_EPI = false, bool SP2 = false>
; __device__ __forceinline__ void gemm_phase(PG8_LAS unsigned char* lds, const Gemm g, const Sched& S, const Epi& E) {
;     ...
;         PG8_STAGE(PG8_SB(0, 0), cB, voffB); PG8_STAGE(PG8_SB(0, 1), cB + hstepB, voffB); PG8_STAGE(PG8_SA(0, 0), cA, voffA); PG8_STAGE(PG8_SA(0, 1), cA + hstepA, voffA);
;         if (wr == 1) PG8_BAR;
;         PG8_WAIT_V(2); PG8_BAR;
;         PG8_STAGE(PG8_SB(1, 0), cB + kstep, voffB); PG8_STAGE(PG8_SA(1, 0), cA + kstep, voffA); PG8_STAGE(PG8_SB(1, 1), cB + hstepB + kstep, voffB);
;         PG8_WAIT_V(6); PG8_BAR;
.LBB0_1367:
	v_lshrrev_b32_e32 v20, 1, v10
	v_and_b32_e32 v20, 24, v20
	v_readlane_b32 s18, v254, 56
	v_and_b32_e32 v11, 15, v10
	v_lshlrev_b32_e32 v21, 1, v20
	v_lshlrev_b32_e32 v10, 2, v10
	s_lshl_b32 s5, s5, 5
	v_mov_b32_e32 v135, v1
	v_readlane_b32 s19, v254, 57
	v_lshl_or_b32 v0, s6, 6, v11
	v_lshl_or_b32 v11, v11, 6, v21
	s_lshl_b32 s6, s6, 13
	v_and_b32_e32 v10, 32, v10
	s_and_b32 s5, s5, 0x60
	v_lshl_add_u64 v[12:13], s[18:19], 0, v[134:135]
	v_mov_b32_e32 v131, v1
	v_readlane_b32 s50, v254, 52
	v_bitop3_b32 v21, v11, s6, v10 bitop3:0xde
	s_lshl_b32 s6, s5, 7
	v_lshl_add_u64 v[14:15], s[18:19], 0, v[130:131]
	v_mov_b32_e32 v137, v1
	v_readlane_b32 s51, v254, 53
	v_bitop3_b32 v142, v11, s6, v10 bitop3:0xde
	s_add_i32 m0, s9, 0x18000
	v_lshl_add_u64 v[10:11], v[12:13], 0, s[20:21]
	v_lshl_add_u64 v[16:17], s[50:51], 0, v[136:137]
	v_mov_b32_e32 v133, v1
	global_load_lds_dwordx4 v[10:11], off
	v_lshl_add_u64 v[10:11], v[14:15], 0, s[20:21]
	s_add_i32 m0, s9, 0x1a000
	s_add_i32 s25, s9, 0x8000
	s_waitcnt lgkmcnt(0)
	v_lshl_add_u64 v[18:19], s[50:51], 0, v[132:133]
	global_load_lds_dwordx4 v[10:11], off
	v_lshl_add_u64 v[10:11], v[16:17], 0, s[20:21]
	s_mov_b32 m0, s25
	s_add_i32 s26, s9, 0xa000
	v_readlane_b32 s6, v254, 58
	global_load_lds_dwordx4 v[10:11], off
	v_lshl_add_u64 v[10:11], v[18:19], 0, s[20:21]
	s_mov_b32 m0, s26
	v_readlane_b32 s7, v254, 59
	global_load_lds_dwordx4 v[10:11], off
	s_add_i32 m0, s9, 0x1c000
	v_lshl_add_u64 v[10:11], s[6:7], 0, v[134:135]
	global_load_lds_dwordx4 v[10:11], off
	v_lshl_add_u64 v[10:11], s[6:7], 0, v[130:131]
	s_add_i32 m0, s9, 0x1e000
	s_movk_i32 s6, 0xb00
	global_load_lds_dwordx4 v[10:11], off
	v_lshrrev_b32_e32 v7, 1, v7
	v_mul_lo_u32 v6, v6, s6
	s_mov_b32 s7, 0xb000
	s_cmpk_lt_u32 s4, 0x100
	v_or_b32_e32 v143, s5, v20
	v_mad_u64_u32 v[6:7], s[4:5], v7, s7, v[6:7]
	v_or_b32_e32 v6, v6, v8
	v_add_lshl_u32 v6, v6, v9, 1
	v_mov_b32_e32 v7, v1
	s_mov_b64 s[28:29], 0xb0080
	v_lshl_add_u64 v[138:139], v[6:7], 0, s[28:29]
	v_lshrrev_b32_e32 v6, 1, v2
	v_mul_lo_u32 v2, v3, s6
	v_mad_u64_u32 v[2:3], s[4:5], v6, s7, v[2:3]
	s_waitcnt vmcnt(8)
	s_barrier
	s_waitcnt vmcnt(6)
	v_or_b32_e32 v2, v2, v4
	v_readlane_b32 s4, v254, 32
	v_add_lshl_u32 v2, v2, v5, 1
	v_mov_b32_e32 v3, v1
	v_readlane_b32 s5, v254, 33
	s_cselect_b64 s[42:43], -1, 0
	v_lshl_add_u64 v[140:141], v[2:3], 0, s[28:29]
	s_mov_b32 s27, 0
	v_add_u32_e32 v144, 0, v21
	v_readlane_b32 s29, v254, 3
	s_mov_b32 s59, s4
	s_mov_b64 s[4:5], s[18:19]
	s_barrier
	s_branch .LBB0_1370

; #define PG8_STAGE(bufoff, gbase, voff) do { _Pragma("unroll") for (int _i = 0; _i < 2; ++_i) \
;         __builtin_amdgcn_global_load_lds((const unsigned*)((const char*)(gbase) + (voff)[_i]), (PG8_LAS unsigned*)(lds + (bufoff) + ldsw + _i * 8192), 16, 0, 0); } while (0)
; #define PG8_WAIT_V(n) asm volatile("s_waitcnt vmcnt(" #n ")" ::: "memory")
; #define PG8_BAR __builtin_amdgcn_s_barrier()
; template <class Epi, class Sched, bool ALIGN_EPI = false, bool SP2 = false>
; __device__ __forceinline__ void gemm_phase(PG8_LAS unsigned char* lds, const Gemm g, const Sched& S, const Epi& E) {
;     ...
;         PG8_STAGE(PG8_SB(0, 0), cB, voffB); PG8_STAGE(PG8_SB(0, 1), cB + hstepB, voffB); PG8_STAGE(PG8_SA(0, 0), cA, voffA); PG8_STAGE(PG8_SA(0, 1), cA + hstepA, voffA);
;         if (wr == 1) PG8_BAR;
;         PG8_WAIT_V(2); PG8_BAR;
;         PG8_STAGE(PG8_SB(1, 0), cB + kstep, voffB); PG8_STAGE(PG8_SA(1, 0), cA + kstep, voffA); PG8_STAGE(PG8_SB(1, 1), cB + hstepB + kstep, voffB);
;         PG8_WAIT_V(6); PG8_BAR;
.LBB0_1389:
	v_lshrrev_b32_e32 v18, 1, v8
	v_and_b32_e32 v18, 24, v18
	v_readlane_b32 s18, v253, 0
	v_and_b32_e32 v9, 15, v8
	s_waitcnt lgkmcnt(0)
	v_lshlrev_b32_e32 v19, 1, v18
	v_lshlrev_b32_e32 v8, 2, v8
	s_lshl_b32 s5, s5, 5
	v_mov_b32_e32 v147, v1
	v_readlane_b32 s19, v253, 1
	v_lshl_or_b32 v0, s6, 6, v9
	v_lshl_or_b32 v9, v9, 6, v19
	s_lshl_b32 s6, s6, 13
	v_and_b32_e32 v8, 32, v8
	s_and_b32 s5, s5, 0x60
	v_lshl_add_u64 v[10:11], s[18:19], 0, v[146:147]
	v_mov_b32_e32 v143, v1
	v_readlane_b32 s8, v254, 38
	v_bitop3_b32 v19, v9, s6, v8 bitop3:0xde
	s_lshl_b32 s6, s5, 7
	v_lshl_add_u64 v[12:13], s[18:19], 0, v[142:143]
	v_mov_b32_e32 v149, v1
	v_readlane_b32 s9, v254, 39
	v_bitop3_b32 v162, v9, s6, v8 bitop3:0xde
	s_add_i32 m0, s68, 0x18000
	v_lshl_add_u64 v[8:9], v[10:11], 0, s[20:21]
	v_lshl_add_u64 v[14:15], s[8:9], 0, v[148:149]
	v_mov_b32_e32 v145, v1
	global_load_lds_dwordx4 v[8:9], off
	v_lshl_add_u64 v[8:9], v[12:13], 0, s[20:21]
	s_add_i32 m0, s68, 0x1a000
	s_add_i32 s74, s68, 0x8000
	v_lshl_add_u64 v[16:17], s[8:9], 0, v[144:145]
	global_load_lds_dwordx4 v[8:9], off
	v_lshl_add_u64 v[8:9], v[14:15], 0, s[20:21]
	s_mov_b32 m0, s74
	s_add_i32 s78, s68, 0xa000
	v_readlane_b32 s6, v253, 2
	global_load_lds_dwordx4 v[8:9], off
	v_lshl_add_u64 v[8:9], v[16:17], 0, s[20:21]
	s_mov_b32 m0, s78
	v_readlane_b32 s7, v253, 3
	global_load_lds_dwordx4 v[8:9], off
	s_add_i32 m0, s68, 0x1c000
	v_lshl_add_u64 v[8:9], s[6:7], 0, v[146:147]
	global_load_lds_dwordx4 v[8:9], off
	v_lshl_add_u64 v[8:9], s[6:7], 0, v[142:143]
	s_add_i32 m0, s68, 0x1e000
	s_cmpk_lt_u32 s4, 0x100
	global_load_lds_dwordx4 v[8:9], off
	v_lshlrev_b32_e32 v8, 14, v6
	v_and_b32_e32 v8, 0xffff8000, v8
	v_lshl_add_u32 v5, v5, 11, v8
	v_and_b32_e32 v6, 1, v6
	v_lshl_or_b32 v5, v6, 6, v5
	v_lshl_add_u32 v150, v7, 1, v5
	v_lshlrev_b32_e32 v5, 14, v2
	v_and_b32_e32 v5, 0xffff8000, v5
	s_waitcnt vmcnt(8)
	s_barrier
	s_waitcnt vmcnt(6)
	v_or_b32_e32 v163, s5, v18
	v_lshl_add_u32 v3, v3, 11, v5
	v_and_b32_e32 v2, 1, v2
	v_readlane_b32 s4, v254, 32
	v_lshl_or_b32 v2, v2, 6, v3
	v_readlane_b32 s5, v254, 33
	s_cselect_b64 s[40:41], -1, 0
	v_mov_b32_e32 v151, v1
	v_lshl_add_u32 v152, v4, 1, v2
	v_mov_b32_e32 v153, v1
	s_mov_b32 s79, 0
	v_add_u32_e32 v164, 0, v19
	v_readlane_b32 s13, v254, 3
	s_mov_b32 s22, s4
	s_mov_b64 s[4:5], s[18:19]
	s_mov_b64 s[6:7], s[8:9]
	s_barrier
	s_branch .LBB0_1392

; #define PG8_STAGE(bufoff, gbase, voff) do { _Pragma("unroll") for (int _i = 0; _i < 2; ++_i) \
;         __builtin_amdgcn_global_load_lds((const unsigned*)((const char*)(gbase) + (voff)[_i]), (PG8_LAS unsigned*)(lds + (bufoff) + ldsw + _i * 8192), 16, 0, 0); } while (0)
; #define PG8_WAIT_V(n) asm volatile("s_waitcnt vmcnt(" #n ")" ::: "memory")
; #define PG8_BAR __builtin_amdgcn_s_barrier()
; template <class Epi, class Sched, bool ALIGN_EPI = false, bool SP2 = false>
; __device__ __forceinline__ void gemm_phase(PG8_LAS unsigned char* lds, const Gemm g, const Sched& S, const Epi& E) {
;     ...
;         PG8_STAGE(PG8_SB(0, 0), cB, voffB); PG8_STAGE(PG8_SB(0, 1), cB + hstepB, voffB); PG8_STAGE(PG8_SA(0, 0), cA, voffA); PG8_STAGE(PG8_SA(0, 1), cA + hstepA, voffA);
;         if (wr == 1) PG8_BAR;
;         PG8_WAIT_V(2); PG8_BAR;
;         PG8_STAGE(PG8_SB(1, 0), cB + kstep, voffB); PG8_STAGE(PG8_SA(1, 0), cA + kstep, voffA); PG8_STAGE(PG8_SB(1, 1), cB + hstepB + kstep, voffB);
;         PG8_WAIT_V(6); PG8_BAR;
.LBB0_1409:
	v_lshrrev_b32_e32 v20, 1, v10
	v_and_b32_e32 v20, 24, v20
	v_readlane_b32 s18, v253, 14
	v_and_b32_e32 v11, 15, v10
	v_lshlrev_b32_e32 v21, 1, v20
	v_lshlrev_b32_e32 v10, 2, v10
	s_lshl_b32 s5, s5, 5
	v_mov_b32_e32 v135, v1
	v_readlane_b32 s19, v253, 15
	v_lshl_or_b32 v0, s6, 6, v11
	v_lshl_or_b32 v11, v11, 6, v21
	s_lshl_b32 s6, s6, 13
	v_and_b32_e32 v10, 32, v10
	s_and_b32 s5, s5, 0x60
	v_lshl_add_u64 v[12:13], s[18:19], 0, v[134:135]
	v_mov_b32_e32 v131, v1
	v_readlane_b32 s50, v253, 10
	v_bitop3_b32 v21, v11, s6, v10 bitop3:0xde
	s_lshl_b32 s6, s5, 7
	v_lshl_add_u64 v[14:15], s[18:19], 0, v[130:131]
	v_mov_b32_e32 v137, v1
	v_readlane_b32 s51, v253, 11
	v_bitop3_b32 v142, v11, s6, v10 bitop3:0xde
	s_add_i32 m0, s9, 0x18000
	v_lshl_add_u64 v[10:11], v[12:13], 0, s[20:21]
	v_lshl_add_u64 v[16:17], s[50:51], 0, v[136:137]
	v_mov_b32_e32 v133, v1
	global_load_lds_dwordx4 v[10:11], off
	v_lshl_add_u64 v[10:11], v[14:15], 0, s[20:21]
	s_add_i32 m0, s9, 0x1a000
	s_add_i32 s25, s9, 0x8000
	s_waitcnt lgkmcnt(0)
	v_lshl_add_u64 v[18:19], s[50:51], 0, v[132:133]
	global_load_lds_dwordx4 v[10:11], off
	v_lshl_add_u64 v[10:11], v[16:17], 0, s[20:21]
	s_mov_b32 m0, s25
	s_add_i32 s26, s9, 0xa000
	v_readlane_b32 s6, v253, 16
	global_load_lds_dwordx4 v[10:11], off
	v_lshl_add_u64 v[10:11], v[18:19], 0, s[20:21]
	s_mov_b32 m0, s26
	v_readlane_b32 s7, v253, 17
	global_load_lds_dwordx4 v[10:11], off
	s_add_i32 m0, s9, 0x1c000
	v_lshl_add_u64 v[10:11], s[6:7], 0, v[134:135]
	global_load_lds_dwordx4 v[10:11], off
	v_lshl_add_u64 v[10:11], s[6:7], 0, v[130:131]
	s_add_i32 m0, s9, 0x1e000
	s_movk_i32 s6, 0xb00
	global_load_lds_dwordx4 v[10:11], off
	v_lshrrev_b32_e32 v7, 1, v7
	v_mul_lo_u32 v6, v6, s6
	s_mov_b32 s7, 0xb000
	s_cmpk_lt_u32 s4, 0x100
	v_or_b32_e32 v143, s5, v20
	v_mad_u64_u32 v[6:7], s[4:5], v7, s7, v[6:7]
	v_or_b32_e32 v6, v6, v8
	v_add_lshl_u32 v6, v6, v9, 1
	v_mov_b32_e32 v7, v1
	s_mov_b64 s[28:29], 0xb0080
	v_lshl_add_u64 v[138:139], v[6:7], 0, s[28:29]
	v_lshrrev_b32_e32 v6, 1, v2
	v_mul_lo_u32 v2, v3, s6
	v_mad_u64_u32 v[2:3], s[4:5], v6, s7, v[2:3]
	s_waitcnt vmcnt(8)
	s_barrier
	s_waitcnt vmcnt(6)
	v_or_b32_e32 v2, v2, v4
	v_readlane_b32 s4, v254, 32
	v_add_lshl_u32 v2, v2, v5, 1
	v_mov_b32_e32 v3, v1
	v_readlane_b32 s5, v254, 33
	s_cselect_b64 s[42:43], -1, 0
	v_lshl_add_u64 v[140:141], v[2:3], 0, s[28:29]
	s_mov_b32 s27, 0
	v_add_u32_e32 v144, 0, v21
	v_readlane_b32 s29, v254, 3
	s_mov_b32 s59, s4
	s_mov_b64 s[4:5], s[18:19]
	s_barrier
	s_branch .LBB0_1412

; #define PG8_STAGE(bufoff, gbase, voff) do { _Pragma("unroll") for (int _i = 0; _i < 2; ++_i) \
;         __builtin_amdgcn_global_load_lds((const unsigned*)((const char*)(gbase) + (voff)[_i]), (PG8_LAS unsigned*)(lds + (bufoff) + ldsw + _i * 8192), 16, 0, 0); } while (0)
; #define PG8_WAIT_V(n) asm volatile("s_waitcnt vmcnt(" #n ")" ::: "memory")
; #define PG8_BAR __builtin_amdgcn_s_barrier()
; template <class Epi, class Sched, bool ALIGN_EPI = false, bool SP2 = false>
; __device__ __forceinline__ void gemm_phase(PG8_LAS unsigned char* lds, const Gemm g, const Sched& S, const Epi& E) {
;     ...
;         PG8_STAGE(PG8_SB(0, 0), cB, voffB); PG8_STAGE(PG8_SB(0, 1), cB + hstepB, voffB); PG8_STAGE(PG8_SA(0, 0), cA, voffA); PG8_STAGE(PG8_SA(0, 1), cA + hstepA, voffA);
;         if (wr == 1) PG8_BAR;
;         PG8_WAIT_V(2); PG8_BAR;
;         PG8_STAGE(PG8_SB(1, 0), cB + kstep, voffB); PG8_STAGE(PG8_SA(1, 0), cA + kstep, voffA); PG8_STAGE(PG8_SB(1, 1), cB + hstepB + kstep, voffB);
;         PG8_WAIT_V(6); PG8_BAR;
.LBB0_1431:
	v_lshrrev_b32_e32 v18, 1, v8
	v_and_b32_e32 v18, 24, v18
	v_readlane_b32 s18, v253, 22
	v_and_b32_e32 v9, 15, v8
	s_waitcnt lgkmcnt(0)
	v_lshlrev_b32_e32 v19, 1, v18
	v_lshlrev_b32_e32 v8, 2, v8
	s_lshl_b32 s5, s5, 5
	v_mov_b32_e32 v167, v1
	v_readlane_b32 s19, v253, 23
	v_lshl_or_b32 v0, s6, 6, v9
	v_lshl_or_b32 v9, v9, 6, v19
	s_lshl_b32 s6, s6, 13
	v_and_b32_e32 v8, 32, v8
	s_and_b32 s5, s5, 0x60
	v_lshl_add_u64 v[10:11], s[18:19], 0, v[166:167]
	v_mov_b32_e32 v163, v1
	v_readlane_b32 s8, v254, 38
	v_bitop3_b32 v19, v9, s6, v8 bitop3:0xde
	s_lshl_b32 s6, s5, 7
	v_lshl_add_u64 v[12:13], s[18:19], 0, v[162:163]
	v_mov_b32_e32 v169, v1
	v_readlane_b32 s9, v254, 39
	v_bitop3_b32 v184, v9, s6, v8 bitop3:0xde
	s_add_i32 m0, s68, 0x18000
	v_lshl_add_u64 v[8:9], v[10:11], 0, s[20:21]
	v_lshl_add_u64 v[14:15], s[8:9], 0, v[168:169]
	v_mov_b32_e32 v165, v1
	global_load_lds_dwordx4 v[8:9], off
	v_lshl_add_u64 v[8:9], v[12:13], 0, s[20:21]
	s_add_i32 m0, s68, 0x1a000
	s_add_i32 s74, s68, 0x8000
	v_lshl_add_u64 v[16:17], s[8:9], 0, v[164:165]
	global_load_lds_dwordx4 v[8:9], off
	v_lshl_add_u64 v[8:9], v[14:15], 0, s[20:21]
	s_mov_b32 m0, s74
	s_add_i32 s78, s68, 0xa000
	v_readlane_b32 s6, v253, 24
	global_load_lds_dwordx4 v[8:9], off
	v_lshl_add_u64 v[8:9], v[16:17], 0, s[20:21]
	s_mov_b32 m0, s78
	v_readlane_b32 s7, v253, 25
	global_load_lds_dwordx4 v[8:9], off
	s_add_i32 m0, s68, 0x1c000
	v_lshl_add_u64 v[8:9], s[6:7], 0, v[166:167]
	global_load_lds_dwordx4 v[8:9], off
	v_lshl_add_u64 v[8:9], s[6:7], 0, v[162:163]
	s_add_i32 m0, s68, 0x1e000
	s_cmpk_lt_u32 s4, 0x100
	global_load_lds_dwordx4 v[8:9], off
	v_lshlrev_b32_e32 v8, 14, v6
	v_and_b32_e32 v8, 0xffff8000, v8
	v_lshl_add_u32 v5, v5, 11, v8
	v_and_b32_e32 v6, 1, v6
	v_lshl_or_b32 v5, v6, 6, v5
	v_lshl_add_u32 v170, v7, 1, v5
	v_lshlrev_b32_e32 v5, 14, v2
	v_and_b32_e32 v5, 0xffff8000, v5
	s_waitcnt vmcnt(8)
	s_barrier
	s_waitcnt vmcnt(6)
	v_or_b32_e32 v185, s5, v18
	v_lshl_add_u32 v3, v3, 11, v5
	v_and_b32_e32 v2, 1, v2
	v_readlane_b32 s4, v254, 32
	v_lshl_or_b32 v2, v2, 6, v3
	v_readlane_b32 s5, v254, 33
	s_cselect_b64 s[40:41], -1, 0
	v_mov_b32_e32 v171, v1
	v_lshl_add_u32 v172, v4, 1, v2
	v_mov_b32_e32 v173, v1
	s_mov_b32 s79, 0
	v_add_u32_e32 v186, 0, v19
	v_readlane_b32 s13, v254, 3
	s_mov_b32 s22, s4
	s_mov_b64 s[4:5], s[18:19]
	s_mov_b64 s[6:7], s[8:9]
	s_barrier
	s_branch .LBB0_1434

; #define PG8_STAGE(bufoff, gbase, voff) do { _Pragma("unroll") for (int _i = 0; _i < 2; ++_i) \
;         __builtin_amdgcn_global_load_lds((const unsigned*)((const char*)(gbase) + (voff)[_i]), (PG8_LAS unsigned*)(lds + (bufoff) + ldsw + _i * 8192), 16, 0, 0); } while (0)
; #define PG8_WAIT_V(n) asm volatile("s_waitcnt vmcnt(" #n ")" ::: "memory")
; #define PG8_BAR __builtin_amdgcn_s_barrier()
; template <class Epi, class Sched, bool ALIGN_EPI = false, bool SP2 = false>
; __device__ __forceinline__ void gemm_phase(PG8_LAS unsigned char* lds, const Gemm g, const Sched& S, const Epi& E) {
;     ...
;         PG8_STAGE(PG8_SB(0, 0), cB, voffB); PG8_STAGE(PG8_SB(0, 1), cB + hstepB, voffB); PG8_STAGE(PG8_SA(0, 0), cA, voffA); PG8_STAGE(PG8_SA(0, 1), cA + hstepA, voffA);
;         if (wr == 1) PG8_BAR;
;         PG8_WAIT_V(2); PG8_BAR;
;         PG8_STAGE(PG8_SB(1, 0), cB + kstep, voffB); PG8_STAGE(PG8_SA(1, 0), cA + kstep, voffA); PG8_STAGE(PG8_SB(1, 1), cB + hstepB + kstep, voffB);
;         PG8_WAIT_V(6); PG8_BAR;
.LBB0_1517:
	v_readlane_b32 s18, v253, 30
	v_mov_b32_e32 v135, v1
	v_readlane_b32 s19, v253, 31
	v_readlane_b32 s26, v255, 28
	v_mov_b32_e32 v131, v1
	v_lshl_add_u64 v[10:11], s[18:19], 0, v[134:135]
	v_readlane_b32 s48, v254, 8
	v_readlane_b32 s27, v255, 29
	s_add_u32 s25, s26, 0x5000
	v_lshl_add_u64 v[12:13], s[18:19], 0, v[130:131]
	v_mov_b32_e32 v137, v1
	v_readlane_b32 s49, v254, 9
	s_addc_u32 s26, s27, 0
	s_add_i32 m0, s9, 0x18000
	v_lshl_add_u64 v[10:11], v[10:11], 0, s[20:21]
	v_lshl_add_u64 v[14:15], s[48:49], 0, v[136:137]
	v_mov_b32_e32 v133, v1
	global_load_lds_dwordx4 v[10:11], off
	v_lshl_add_u64 v[10:11], v[12:13], 0, s[20:21]
	s_add_i32 m0, s9, 0x1a000
	s_add_i32 s27, s9, 0x8000
	v_lshl_add_u64 v[16:17], s[48:49], 0, v[132:133]
	global_load_lds_dwordx4 v[10:11], off
	v_lshl_add_u64 v[10:11], v[14:15], 0, s[20:21]
	s_mov_b32 m0, s27
	s_add_i32 s28, s9, 0xa000
	v_readlane_b32 s38, v253, 32
	global_load_lds_dwordx4 v[10:11], off
	v_lshl_add_u64 v[10:11], v[16:17], 0, s[20:21]
	s_mov_b32 m0, s28
	v_readlane_b32 s39, v253, 33
	global_load_lds_dwordx4 v[10:11], off
	s_add_i32 m0, s9, 0x1c000
	v_lshl_add_u64 v[10:11], s[38:39], 0, v[134:135]
	global_load_lds_dwordx4 v[10:11], off
	v_lshl_add_u64 v[10:11], s[38:39], 0, v[130:131]
	s_add_i32 m0, s9, 0x1e000
	v_bfe_u32 v14, v0, 4, 2
	global_load_lds_dwordx4 v[10:11], off
	v_and_b32_e32 v15, 15, v0
	s_lshl_b32 s7, s6, 6
	v_lshlrev_b32_e32 v11, 4, v14
	v_lshlrev_b32_e32 v0, 2, v0
	s_lshl_b32 s5, s5, 5
	v_or_b32_e32 v10, s7, v15
	v_lshl_or_b32 v11, v15, 6, v11
	s_lshl_b32 s6, s6, 13
	v_and_b32_e32 v0, 32, v0
	s_and_b32 s5, s5, 0x60
	v_bitop3_b32 v16, v11, s6, v0 bitop3:0xde
	s_lshl_b32 s6, s5, 7
	v_or_b32_e32 v12, 16, v10
	v_bitop3_b32 v0, v11, s6, v0 bitop3:0xde
	v_ashrrev_i32_e32 v11, 31, v10
	v_ashrrev_i32_e32 v13, 31, v12
	s_cmpk_lt_u32 s4, 0x100
	v_lshlrev_b64 v[138:139], 12, v[10:11]
	v_lshlrev_b64 v[140:141], 12, v[12:13]
	v_or_b32_e32 v12, 32, v10
	v_or_b32_e32 v10, 48, v10
	s_cselect_b64 s[42:43], -1, 0
	v_ashrrev_i32_e32 v11, 31, v10
	s_addk_i32 s7, 0x80
	v_ashrrev_i32_e32 v13, 31, v12
	v_lshlrev_b64 v[144:145], 12, v[10:11]
	v_or_b32_e32 v10, s7, v15
	v_lshlrev_b64 v[142:143], 12, v[12:13]
	v_or_b32_e32 v12, 16, v10
	v_ashrrev_i32_e32 v11, 31, v10
	v_ashrrev_i32_e32 v13, 31, v12
	v_lshlrev_b64 v[146:147], 12, v[10:11]
	v_lshlrev_b64 v[148:149], 12, v[12:13]
	v_or_b32_e32 v12, 32, v10
	v_or_b32_e32 v10, 48, v10
	v_ashrrev_i32_e32 v11, 31, v10
	s_movk_i32 s6, 0xb00
	v_lshlrev_b64 v[152:153], 12, v[10:11]
	v_lshrrev_b32_e32 v7, 1, v7
	v_mul_lo_u32 v10, v9, s6
	s_mov_b32 s7, 0xb000
	v_lshl_or_b32 v176, v14, 2, s5
	v_mad_u64_u32 v[10:11], s[4:5], v7, s7, v[10:11]
	v_or_b32_e32 v6, v10, v6
	v_add_lshl_u32 v6, v6, v8, 1
	v_mov_b32_e32 v7, v1
	s_mov_b64 s[38:39], 0xb0080
	v_lshl_add_u64 v[154:155], v[6:7], 0, s[38:39]
	v_lshrrev_b32_e32 v3, 1, v3
	v_mul_lo_u32 v6, v5, s6
	v_mad_u64_u32 v[6:7], s[4:5], v3, s7, v[6:7]
	s_waitcnt vmcnt(8)
	s_barrier
	s_waitcnt vmcnt(6)
	v_or_b32_e32 v2, v6, v2
	v_readlane_b32 s4, v254, 32
	v_ashrrev_i32_e32 v13, 31, v12
	v_add_lshl_u32 v2, v2, v4, 1
	v_mov_b32_e32 v3, v1
	v_readlane_b32 s5, v254, 33
	v_lshlrev_b64 v[150:151], 12, v[12:13]
	v_lshl_add_u64 v[156:157], v[2:3], 0, s[38:39]
	s_mov_b32 s29, 0
	v_add_u32_e32 v177, 0, v16
	v_readlane_b32 s64, v254, 3
	s_mov_b32 s68, s4
	s_mov_b64 s[4:5], s[18:19]
	s_barrier
	s_branch .LBB0_1520

; #define PG8_STAGE(bufoff, gbase, voff) do { _Pragma("unroll") for (int _i = 0; _i < 2; ++_i) \
;         __builtin_amdgcn_global_load_lds((const unsigned*)((const char*)(gbase) + (voff)[_i]), (PG8_LAS unsigned*)(lds + (bufoff) + ldsw + _i * 8192), 16, 0, 0); } while (0)
; #define PG8_WAIT_V(n) asm volatile("s_waitcnt vmcnt(" #n ")" ::: "memory")
; #define PG8_BAR __builtin_amdgcn_s_barrier()
; template <class Epi, class Sched, bool ALIGN_EPI = false, bool SP2 = false>
; __device__ __forceinline__ void gemm_phase(PG8_LAS unsigned char* lds, const Gemm g, const Sched& S, const Epi& E) {
;     ...
;         PG8_STAGE(PG8_SB(0, 0), cB, voffB); PG8_STAGE(PG8_SB(0, 1), cB + hstepB, voffB); PG8_STAGE(PG8_SA(0, 0), cA, voffA); PG8_STAGE(PG8_SA(0, 1), cA + hstepA, voffA);
;         if (wr == 1) PG8_BAR;
;         PG8_WAIT_V(2); PG8_BAR;
;         PG8_STAGE(PG8_SB(1, 0), cB + kstep, voffB); PG8_STAGE(PG8_SA(1, 0), cA + kstep, voffA); PG8_STAGE(PG8_SB(1, 1), cB + hstepB + kstep, voffB);
;         PG8_WAIT_V(6); PG8_BAR;
.LBB0_1658:
	v_lshrrev_b32_e32 v18, 1, v16
	v_and_b32_e32 v18, 24, v18
	v_and_b32_e32 v17, 15, v16
	s_waitcnt lgkmcnt(0)
	v_lshlrev_b32_e32 v19, 1, v18
	v_lshlrev_b32_e32 v16, 2, v16
	s_sext_i32_i16 s13, s4
	v_lshl_or_b32 v0, s7, 6, v17
	v_lshl_or_b32 v17, v17, 6, v19
	s_lshl_b32 s4, s7, 13
	v_and_b32_e32 v16, 32, v16
	v_bitop3_b32 v19, v17, s4, v16 bitop3:0xde
	s_lshl_b32 s4, s6, 5
	s_and_b32 s4, s4, 0x60
	s_add_i32 m0, s49, 0x18000
	v_lshl_add_u64 v[8:9], v[8:9], 0, s[20:21]
	s_lshl_b32 s6, s4, 7
	global_load_lds_dwordx4 v[8:9], off
	v_lshl_add_u64 v[6:7], v[6:7], 0, s[20:21]
	s_add_i32 m0, s49, 0x1a000
	s_add_i32 s81, s49, 0x8000
	s_add_i32 s94, s49, 0xa000
	v_bitop3_b32 v142, v17, s6, v16 bitop3:0xde
	global_load_lds_dwordx4 v[6:7], off
	v_lshl_add_u64 v[2:3], v[2:3], 0, s[20:21]
	s_mov_b32 m0, s81
	s_add_u32 s6, s72, 0x40080
	global_load_lds_dwordx4 v[2:3], off
	v_lshl_add_u64 v[2:3], v[4:5], 0, s[20:21]
	s_mov_b32 m0, s94
	s_addc_u32 s7, s73, 0
	global_load_lds_dwordx4 v[2:3], off
	s_add_i32 m0, s49, 0x1c000
	v_lshl_add_u64 v[2:3], s[6:7], 0, v[134:135]
	global_load_lds_dwordx4 v[2:3], off
	v_lshl_add_u64 v[2:3], s[6:7], 0, v[130:131]
	s_add_i32 m0, s49, 0x1e000
	s_cmpk_lt_u32 s5, 0x100
	global_load_lds_dwordx4 v[2:3], off
	v_lshlrev_b32_e32 v2, 14, v14
	v_and_b32_e32 v2, 0xffff8000, v2
	v_lshl_add_u32 v2, v13, 11, v2
	v_and_b32_e32 v3, 1, v14
	v_lshl_or_b32 v2, v3, 6, v2
	v_lshl_add_u32 v138, v15, 1, v2
	v_lshlrev_b32_e32 v2, 14, v10
	v_and_b32_e32 v2, 0xffff8000, v2
	s_waitcnt vmcnt(8)
	s_barrier
	s_waitcnt vmcnt(6)
	v_lshl_add_u32 v2, v11, 11, v2
	v_and_b32_e32 v3, 1, v10
	v_lshl_or_b32 v2, v3, 6, v2
	s_cselect_b64 s[40:41], -1, 0
	v_or_b32_e32 v143, s4, v18
	v_mov_b32_e32 v139, v1
	v_lshl_add_u32 v140, v12, 1, v2
	v_mov_b32_e32 v141, v1
	s_mov_b32 s95, 0
	v_add_u32_e32 v144, 0, v19
	s_barrier
	s_branch .LBB0_1661

; #define PG8_STAGE(bufoff, gbase, voff) do { _Pragma("unroll") for (int _i = 0; _i < 2; ++_i) \
;         __builtin_amdgcn_global_load_lds((const unsigned*)((const char*)(gbase) + (voff)[_i]), (PG8_LAS unsigned*)(lds + (bufoff) + ldsw + _i * 8192), 16, 0, 0); } while (0)
; #define PG8_WAIT_V(n) asm volatile("s_waitcnt vmcnt(" #n ")" ::: "memory")
; #define PG8_BAR __builtin_amdgcn_s_barrier()
; template <class Epi, class Sched, bool ALIGN_EPI = false, bool SP2 = false>
; __device__ __forceinline__ void gemm_phase(PG8_LAS unsigned char* lds, const Gemm g, const Sched& S, const Epi& E) {
;     ...
;         PG8_STAGE(PG8_SB(0, 0), cB, voffB); PG8_STAGE(PG8_SB(0, 1), cB + hstepB, voffB); PG8_STAGE(PG8_SA(0, 0), cA, voffA); PG8_STAGE(PG8_SA(0, 1), cA + hstepA, voffA);
;         if (wr == 1) PG8_BAR;
;         PG8_WAIT_V(2); PG8_BAR;
;         PG8_STAGE(PG8_SB(1, 0), cB + kstep, voffB); PG8_STAGE(PG8_SA(1, 0), cA + kstep, voffA); PG8_STAGE(PG8_SB(1, 1), cB + hstepB + kstep, voffB);
;         PG8_WAIT_V(6); PG8_BAR;
.LBB0_1863:
	v_readlane_b32 s18, v253, 38
	v_mov_b32_e32 v133, v1
	v_readlane_b32 s19, v253, 39
	v_readlane_b32 s24, v255, 28
	v_mov_b32_e32 v131, v1
	v_lshl_add_u64 v[10:11], s[18:19], 0, v[132:133]
	v_readlane_b32 s46, v254, 8
	v_readlane_b32 s25, v255, 29
	s_add_u32 s24, s24, 0x8000
	v_lshl_add_u64 v[12:13], s[18:19], 0, v[130:131]
	v_readlane_b32 s47, v254, 9
	s_addc_u32 s25, s25, 0
	s_add_i32 m0, s9, 0x18000
	v_lshl_add_u64 v[10:11], v[10:11], 0, s[20:21]
	v_lshl_add_u64 v[14:15], s[46:47], 0, v[132:133]
	global_load_lds_dwordx4 v[10:11], off
	v_lshl_add_u64 v[10:11], v[12:13], 0, s[20:21]
	s_add_i32 m0, s9, 0x1a000
	s_add_i32 s26, s9, 0x8000
	v_lshl_add_u64 v[16:17], s[46:47], 0, v[130:131]
	global_load_lds_dwordx4 v[10:11], off
	v_lshl_add_u64 v[10:11], v[14:15], 0, s[20:21]
	s_mov_b32 m0, s26
	s_add_i32 s27, s9, 0xa000
	v_readlane_b32 s28, v253, 40
	global_load_lds_dwordx4 v[10:11], off
	v_lshl_add_u64 v[10:11], v[16:17], 0, s[20:21]
	s_mov_b32 m0, s27
	v_readlane_b32 s29, v253, 41
	global_load_lds_dwordx4 v[10:11], off
	s_add_i32 m0, s9, 0x1c000
	v_lshl_add_u64 v[10:11], s[28:29], 0, v[132:133]
	global_load_lds_dwordx4 v[10:11], off
	v_lshl_add_u64 v[10:11], s[28:29], 0, v[130:131]
	s_add_i32 m0, s9, 0x1e000
	v_bfe_u32 v14, v0, 4, 2
	global_load_lds_dwordx4 v[10:11], off
	v_and_b32_e32 v15, 15, v0
	s_lshl_b32 s7, s6, 6
	v_lshlrev_b32_e32 v11, 4, v14
	v_lshlrev_b32_e32 v0, 2, v0
	s_lshl_b32 s5, s5, 5
	v_or_b32_e32 v10, s7, v15
	v_lshl_or_b32 v11, v15, 6, v11
	s_lshl_b32 s6, s6, 13
	v_and_b32_e32 v0, 32, v0
	s_and_b32 s5, s5, 0x60
	v_bitop3_b32 v16, v11, s6, v0 bitop3:0xde
	s_lshl_b32 s6, s5, 7
	v_or_b32_e32 v12, 16, v10
	v_bitop3_b32 v0, v11, s6, v0 bitop3:0xde
	v_ashrrev_i32_e32 v11, 31, v10
	v_ashrrev_i32_e32 v13, 31, v12
	s_cmpk_lt_u32 s4, 0x100
	v_lshlrev_b64 v[134:135], 12, v[10:11]
	v_lshlrev_b64 v[136:137], 12, v[12:13]
	v_or_b32_e32 v12, 32, v10
	v_or_b32_e32 v10, 48, v10
	s_cselect_b64 s[42:43], -1, 0
	v_ashrrev_i32_e32 v11, 31, v10
	s_addk_i32 s7, 0x80
	s_movk_i32 s6, 0xb00
	v_lshlrev_b64 v[140:141], 12, v[10:11]
	v_or_b32_e32 v10, s7, v15
	v_lshrrev_b32_e32 v7, 1, v7
	v_mul_lo_u32 v6, v6, s6
	s_mov_b32 s7, 0xb000
	v_lshl_or_b32 v172, v14, 2, s5
	v_mad_u64_u32 v[6:7], s[4:5], v7, s7, v[6:7]
	v_or_b32_e32 v6, v6, v8
	v_ashrrev_i32_e32 v13, 31, v12
	v_add_lshl_u32 v6, v6, v9, 1
	v_mov_b32_e32 v7, v1
	s_mov_b64 s[28:29], 0xb0080
	v_lshlrev_b64 v[138:139], 12, v[12:13]
	v_or_b32_e32 v12, 16, v10
	v_lshl_add_u64 v[150:151], v[6:7], 0, s[28:29]
	v_lshrrev_b32_e32 v6, 1, v2
	v_mul_lo_u32 v2, v3, s6
	v_ashrrev_i32_e32 v11, 31, v10
	v_ashrrev_i32_e32 v13, 31, v12
	v_mad_u64_u32 v[2:3], s[4:5], v6, s7, v[2:3]
	s_waitcnt vmcnt(8)
	s_barrier
	s_waitcnt vmcnt(6)
	v_lshlrev_b64 v[142:143], 12, v[10:11]
	v_lshlrev_b64 v[144:145], 12, v[12:13]
	v_or_b32_e32 v12, 32, v10
	v_or_b32_e32 v10, 48, v10
	v_or_b32_e32 v2, v2, v4
	v_readlane_b32 s4, v254, 32
	v_ashrrev_i32_e32 v13, 31, v12
	v_ashrrev_i32_e32 v11, 31, v10
	v_add_lshl_u32 v2, v2, v5, 1
	v_mov_b32_e32 v3, v1
	v_readlane_b32 s5, v254, 33
	v_lshlrev_b64 v[146:147], 12, v[12:13]
	v_lshlrev_b64 v[148:149], 12, v[10:11]
	v_lshl_add_u64 v[152:153], v[2:3], 0, s[28:29]
	s_mov_b32 s28, 0
	v_add_u32_e32 v173, 0, v16
	v_readlane_b32 s51, v254, 3
	s_mov_b32 s59, s4
	s_mov_b64 s[4:5], s[18:19]
	s_barrier
	s_branch .LBB0_1866
